# v028 + NSA attention loops: the first tile's 8 K-fragment LDS reads are issued at the loop top right after the barrier, ahead of the flag/prefetch code
# speedup vs baseline: 1.0148x; 1.0037x over previous
; #define LAS __attribute__((address_space(3)))
;     __device__ __forceinline__ bool skip(int t) const { const int nb = t >> 2; if (nb >= qb) return 64 * (t & 3) > wq0 + 31; return !__any((int)((sel >> nb) & 1u)); }
; template <bool HAS_POST, class MaskF>
; __device__ __forceinline__ void attn_run(LAS unsigned char* lds, const bf16* Kg, const bf16* Vg, int pitch, int t0, int t1,
;                                          const bf16x8 (&qr)[4], f32x16& o0, f32x16& o1, f32x16& o2, MaskF& mf, const int wv) {
;     ...
;     for (int ts = t0; ts < t1; ts += 2) {
;         const int cur = ((ts - t0) >> 1) & 1;
;         const bool more = (ts + 2 < t1), more2 = (ts + 3 < t1);
;         if (more) { kp += 2 * tstride; kreg0 = *(const v4u*)kp; vp += 2 * tstride; vreg0 = *(const v4u*)vp;
;             if (more2) { kreg1 = *(const v4u*)(kp + tstride); vreg1 = *(const v4u*)(vp + tstride); } }
; #pragma unroll
;         for (int j = 0; j < 2; ++j) {
;             const int t = ts + j;
;             if (t >= t1) break;
;             if (mf.skip(t)) continue;
;             f32x16 p0, p1; const f32x16 zc = {};
;             LAS unsigned char* Kb = lds + (cur * 2 + j) * KBUF + cx.kroff;
;             if (wv < 4) __builtin_amdgcn_s_setprio(1);
; #pragma unroll
;             for (int d0 = 0; d0 < 4; ++d0) {
;                 const bf16x8 a0 = *(const LAS bf16x8*)(Kb + d0 * 32), a1 = *(const LAS bf16x8*)(Kb + 32 * 144 + d0 * 32);
.LBB0_851:
	s_add_i32 s99, s16, -2
	s_and_b32 s99, s99, 2
	s_mul_i32 s98, s99, 0x2400
	v_add_u32_e32 v106, s98, v167
	ds_read_b128 v[102:105], v106
	ds_read_b128 v[110:113], v106 offset:32
	ds_read_b128 v[50:53], v106 offset:4608
	ds_read_b128 v[132:135], v106 offset:4640
	ds_read_b128 v[136:139], v106 offset:64
	ds_read_b128 v[140:143], v106 offset:4672
	ds_read_b128 v[144:147], v106 offset:96
	ds_read_b128 v[148:151], v106 offset:4704
	s_add_i32 s0, s16, -2
	s_cmp_lt_i32 s16, s34
	s_cselect_b64 s[14:15], -1, 0
	s_cmp_ge_i32 s16, s34
	s_cselect_b64 s[12:13], -1, 0
	s_cmp_lt_i32 s0, s22
	s_cselect_b64 s[4:5], -1, 0
	s_cselect_b64 s[6:7], 0, exec
	s_and_b64 vcc, exec, s[12:13]
	s_cbranch_vccnz .LBB0_855
	s_mov_b64 s[4:5], 0x4000
	v_lshl_add_u64 v[154:155], v[154:155], 0, s[4:5]
	v_lshl_add_u64 v[156:157], v[156:157], 0, s[4:5]
	global_load_dwordx4 v[82:85], v[154:155], off
	global_load_dwordx4 v[86:89], v[156:157], off
	s_and_b64 vcc, exec, s[6:7]
	s_cbranch_vccnz .LBB0_854
	s_mov_b64 s[4:5], 0x2000
	v_lshl_add_u64 v[228:229], v[154:155], 0, s[4:5]
	global_load_dwordx4 v[90:93], v[228:229], off
	v_lshl_add_u64 v[228:229], v[156:157], 0, s[4:5]
	global_load_dwordx4 v[94:97], v[228:229], off

; #define LAS __attribute__((address_space(3)))
; template <bool HAS_POST, class MaskF>
; __device__ __forceinline__ void attn_run(LAS unsigned char* lds, const bf16* Kg, const bf16* Vg, int pitch, int t0, int t1,
;                                          const bf16x8 (&qr)[4], f32x16& o0, f32x16& o1, f32x16& o2, MaskF& mf, const int wv) {
;     ...
;             LAS unsigned char* Kb = lds + (cur * 2 + j) * KBUF + cx.kroff;
;             if (wv < 4) __builtin_amdgcn_s_setprio(1);
; #pragma unroll
;             for (int d0 = 0; d0 < 4; ++d0) {
;                 const bf16x8 a0 = *(const LAS bf16x8*)(Kb + d0 * 32), a1 = *(const LAS bf16x8*)(Kb + 32 * 144 + d0 * 32);
;                 if (d0 == 0) { p0 = __builtin_amdgcn_mfma_f32_32x32x16_bf16(a0, qr[0], zc, 0, 0, 0); p1 = __builtin_amdgcn_mfma_f32_32x32x16_bf16(a1, qr[0], zc, 0, 0, 0); }
;                 else { p0 = __builtin_amdgcn_mfma_f32_32x32x16_bf16(a0, qr[d0], p0, 0, 0, 0); p1 = __builtin_amdgcn_mfma_f32_32x32x16_bf16(a1, qr[d0], p1, 0, 0, 0); }
;             }
.LBB0_858:
	s_and_b64 vcc, exec, s[8:9]
	s_waitcnt lgkmcnt(7)
	v_mfma_f32_32x32x16_bf16 v[66:81], v[102:105], v[116:119], 0
	s_waitcnt lgkmcnt(6)
	v_mfma_f32_32x32x16_bf16 v[66:81], v[110:113], v[120:123], v[66:81]
	s_waitcnt lgkmcnt(5)
	v_mfma_f32_32x32x16_bf16 v[50:65], v[50:53], v[116:119], 0
	s_waitcnt lgkmcnt(4)
	v_mfma_f32_32x32x16_bf16 v[50:65], v[132:135], v[120:123], v[50:65]
	s_waitcnt lgkmcnt(3)
	v_mfma_f32_32x32x16_bf16 v[66:81], v[136:139], v[124:127], v[66:81]
	s_waitcnt lgkmcnt(2)
	v_mfma_f32_32x32x16_bf16 v[50:65], v[140:143], v[124:127], v[50:65]
	s_waitcnt lgkmcnt(1)
	v_mfma_f32_32x32x16_bf16 v[66:81], v[144:147], v[128:131], v[66:81]
	s_waitcnt lgkmcnt(0)
	v_mfma_f32_32x32x16_bf16 v[50:65], v[148:151], v[128:131], v[50:65]
	s_cbranch_vccnz .LBB0_860
	s_setprio 0

; #define LAS __attribute__((address_space(3)))
;     __device__ __forceinline__ bool skip(int t) const { const int nb = t >> 2; if (nb >= qb) return 64 * (t & 3) > wq0 + 31; return !__any((int)((sel >> nb) & 1u)); }
; template <bool HAS_POST, class MaskF>
; __device__ __forceinline__ void attn_run(LAS unsigned char* lds, const bf16* Kg, const bf16* Vg, int pitch, int t0, int t1,
;                                          const bf16x8 (&qr)[4], f32x16& o0, f32x16& o1, f32x16& o2, MaskF& mf, const int wv) {
;     ...
;     for (int ts = t0; ts < t1; ts += 2) {
;         const int cur = ((ts - t0) >> 1) & 1;
;         const bool more = (ts + 2 < t1), more2 = (ts + 3 < t1);
;         if (more) { kp += 2 * tstride; kreg0 = *(const v4u*)kp; vp += 2 * tstride; vreg0 = *(const v4u*)vp;
;             if (more2) { kreg1 = *(const v4u*)(kp + tstride); vreg1 = *(const v4u*)(vp + tstride); } }
; #pragma unroll
;         for (int j = 0; j < 2; ++j) {
;             const int t = ts + j;
;             if (t >= t1) break;
;             if (mf.skip(t)) continue;
;             f32x16 p0, p1; const f32x16 zc = {};
;             LAS unsigned char* Kb = lds + (cur * 2 + j) * KBUF + cx.kroff;
;             if (wv < 4) __builtin_amdgcn_s_setprio(1);
; #pragma unroll
;             for (int d0 = 0; d0 < 4; ++d0) {
;                 const bf16x8 a0 = *(const LAS bf16x8*)(Kb + d0 * 32), a1 = *(const LAS bf16x8*)(Kb + 32 * 144 + d0 * 32);
.LBB0_921:
	s_and_b32 s99, s4, 2
	s_mul_i32 s98, s99, 0x2400
	v_add_u32_e32 v168, s98, v166
	ds_read_b128 v[50:53], v168
	ds_read_b128 v[102:105], v168 offset:32
	ds_read_b128 v[66:69], v168 offset:4608
	ds_read_b128 v[106:109], v168 offset:4640
	ds_read_b128 v[110:113], v168 offset:64
	ds_read_b128 v[132:135], v168 offset:4672
	ds_read_b128 v[136:139], v168 offset:96
	ds_read_b128 v[140:143], v168 offset:4704
	s_add_u32 s94, s4, 2
	s_addc_u32 s95, s5, 0
	s_cmp_gt_i32 s94, s38
	s_cselect_b64 s[20:21], -1, 0
	s_cmp_le_i32 s94, s38
	s_cselect_b64 s[96:97], -1, 0
	s_cmp_lt_i32 s4, s23
	s_cselect_b64 s[0:1], -1, 0
	s_cselect_b64 s[92:93], 0, exec
	s_and_b64 vcc, exec, s[20:21]
	s_cbranch_vccnz .LBB0_925
	s_mov_b64 s[0:1], 0xc0000
	v_lshl_add_u64 v[154:155], v[154:155], 0, s[0:1]
	v_lshl_add_u64 v[156:157], v[156:157], 0, s[0:1]
	global_load_dwordx4 v[82:85], v[154:155], off
	global_load_dwordx4 v[86:89], v[156:157], off
	s_and_b64 vcc, exec, s[92:93]
	s_cbranch_vccnz .LBB0_924
	s_mov_b64 s[0:1], 0x60000
	v_lshl_add_u64 v[228:229], v[154:155], 0, s[0:1]
	global_load_dwordx4 v[90:93], v[228:229], off
	v_lshl_add_u64 v[228:229], v[156:157], 0, s[0:1]
	global_load_dwordx4 v[94:97], v[228:229], off

; #define LAS __attribute__((address_space(3)))
; template <bool HAS_POST, class MaskF>
; __device__ __forceinline__ void attn_run(LAS unsigned char* lds, const bf16* Kg, const bf16* Vg, int pitch, int t0, int t1,
;                                          const bf16x8 (&qr)[4], f32x16& o0, f32x16& o1, f32x16& o2, MaskF& mf, const int wv) {
;     ...
;             LAS unsigned char* Kb = lds + (cur * 2 + j) * KBUF + cx.kroff;
;             if (wv < 4) __builtin_amdgcn_s_setprio(1);
; #pragma unroll
;             for (int d0 = 0; d0 < 4; ++d0) {
;                 const bf16x8 a0 = *(const LAS bf16x8*)(Kb + d0 * 32), a1 = *(const LAS bf16x8*)(Kb + 32 * 144 + d0 * 32);
;                 if (d0 == 0) { p0 = __builtin_amdgcn_mfma_f32_32x32x16_bf16(a0, qr[0], zc, 0, 0, 0); p1 = __builtin_amdgcn_mfma_f32_32x32x16_bf16(a1, qr[0], zc, 0, 0, 0); }
;                 else { p0 = __builtin_amdgcn_mfma_f32_32x32x16_bf16(a0, qr[d0], p0, 0, 0, 0); p1 = __builtin_amdgcn_mfma_f32_32x32x16_bf16(a1, qr[d0], p1, 0, 0, 0); }
;             }
.LBB0_928:
	s_and_b64 vcc, exec, s[18:19]
	s_waitcnt lgkmcnt(7)
	v_mfma_f32_32x32x16_bf16 v[50:65], v[50:53], v[116:119], 0
	s_waitcnt lgkmcnt(6)
	v_mfma_f32_32x32x16_bf16 v[50:65], v[102:105], v[120:123], v[50:65]
	s_waitcnt lgkmcnt(5)
	v_mfma_f32_32x32x16_bf16 v[66:81], v[66:69], v[116:119], 0
	s_waitcnt lgkmcnt(4)
	v_mfma_f32_32x32x16_bf16 v[66:81], v[106:109], v[120:123], v[66:81]
	s_waitcnt lgkmcnt(3)
	v_mfma_f32_32x32x16_bf16 v[50:65], v[110:113], v[124:127], v[50:65]
	s_waitcnt lgkmcnt(2)
	v_mfma_f32_32x32x16_bf16 v[66:81], v[132:135], v[124:127], v[66:81]
	s_waitcnt lgkmcnt(1)
	v_mfma_f32_32x32x16_bf16 v[50:65], v[136:139], v[128:131], v[50:65]
	s_waitcnt lgkmcnt(0)
	v_mfma_f32_32x32x16_bf16 v[66:81], v[140:143], v[128:131], v[66:81]
	s_cbranch_vccnz .LBB0_930
	s_setprio 0

; #define LAS __attribute__((address_space(3)))
;     __device__ __forceinline__ bool skip(int t) const { const int nb = t >> 2; if (nb >= qb) return 64 * (t & 3) > wq0 + 31; return !__any((int)((sel >> nb) & 1u)); }
; template <bool HAS_POST, class MaskF>
; __device__ __forceinline__ void attn_run(LAS unsigned char* lds, const bf16* Kg, const bf16* Vg, int pitch, int t0, int t1,
;                                          const bf16x8 (&qr)[4], f32x16& o0, f32x16& o1, f32x16& o2, MaskF& mf, const int wv) {
;     ...
;     for (int ts = t0; ts < t1; ts += 2) {
;         const int cur = ((ts - t0) >> 1) & 1;
;         const bool more = (ts + 2 < t1), more2 = (ts + 3 < t1);
;         if (more) { kp += 2 * tstride; kreg0 = *(const v4u*)kp; vp += 2 * tstride; vreg0 = *(const v4u*)vp;
;             if (more2) { kreg1 = *(const v4u*)(kp + tstride); vreg1 = *(const v4u*)(vp + tstride); } }
; #pragma unroll
;         for (int j = 0; j < 2; ++j) {
;             const int t = ts + j;
;             if (t >= t1) break;
;             if (mf.skip(t)) continue;
;             f32x16 p0, p1; const f32x16 zc = {};
;             LAS unsigned char* Kb = lds + (cur * 2 + j) * KBUF + cx.kroff;
;             if (wv < 4) __builtin_amdgcn_s_setprio(1);
; #pragma unroll
;             for (int d0 = 0; d0 < 4; ++d0) {
;                 const bf16x8 a0 = *(const LAS bf16x8*)(Kb + d0 * 32), a1 = *(const LAS bf16x8*)(Kb + 32 * 144 + d0 * 32);
.LBB0_960:
	s_add_i32 s99, s96, -8
	s_and_b32 s99, s99, 2
	s_mul_i32 s98, s99, 0x2400
	v_add_u32_e32 v54, s98, v207
	ds_read_b128 v[152:155], v54
	ds_read_b128 v[156:159], v54 offset:4608
	ds_read_b128 v[160:163], v54 offset:32
	ds_read_b128 v[164:167], v54 offset:4640
	ds_read_b128 v[168:171], v54 offset:64
	ds_read_b128 v[172:175], v54 offset:4672
	ds_read_b128 v[176:179], v54 offset:96
	ds_read_b128 v[180:183], v54 offset:4704
	s_add_i32 s1, s3, s96
	s_add_i32 s0, s1, -8
	s_add_i32 s1, s1, -6
	s_cmp_le_i32 s1, s38
	s_cselect_b64 s[20:21], -1, 0
	s_cmp_lt_i32 s0, s23
	s_cselect_b64 s[4:5], -1, 0
	s_cselect_b64 s[94:95], 0, exec
	s_cmp_gt_i32 s1, s38
	s_cbranch_scc1 .LBB0_964
	s_mov_b64 s[4:5], 0xc0000
	v_lshl_add_u64 v[198:199], v[198:199], 0, s[4:5]
	v_lshl_add_u64 v[200:201], v[200:201], 0, s[4:5]
	global_load_dwordx4 v[132:135], v[198:199], off
	global_load_dwordx4 v[136:139], v[200:201], off
	s_and_b64 vcc, exec, s[94:95]
	s_cbranch_vccnz .LBB0_963
	s_mov_b64 s[4:5], 0x60000
	v_lshl_add_u64 v[228:229], v[198:199], 0, s[4:5]
	global_load_dwordx4 v[140:143], v[228:229], off
	v_lshl_add_u64 v[228:229], v[200:201], 0, s[4:5]
	global_load_dwordx4 v[144:147], v[228:229], off

; #define LAS __attribute__((address_space(3)))
; template <bool HAS_POST, class MaskF>
; __device__ __forceinline__ void attn_run(LAS unsigned char* lds, const bf16* Kg, const bf16* Vg, int pitch, int t0, int t1,
;                                          const bf16x8 (&qr)[4], f32x16& o0, f32x16& o1, f32x16& o2, MaskF& mf, const int wv) {
;     ...
;             LAS unsigned char* Kb = lds + (cur * 2 + j) * KBUF + cx.kroff;
;             if (wv < 4) __builtin_amdgcn_s_setprio(1);
; #pragma unroll
;             for (int d0 = 0; d0 < 4; ++d0) {
;                 const bf16x8 a0 = *(const LAS bf16x8*)(Kb + d0 * 32), a1 = *(const LAS bf16x8*)(Kb + 32 * 144 + d0 * 32);
;                 if (d0 == 0) { p0 = __builtin_amdgcn_mfma_f32_32x32x16_bf16(a0, qr[0], zc, 0, 0, 0); p1 = __builtin_amdgcn_mfma_f32_32x32x16_bf16(a1, qr[0], zc, 0, 0, 0); }
;                 else { p0 = __builtin_amdgcn_mfma_f32_32x32x16_bf16(a0, qr[d0], p0, 0, 0, 0); p1 = __builtin_amdgcn_mfma_f32_32x32x16_bf16(a1, qr[d0], p1, 0, 0, 0); }
;             }
.LBB0_966:
	s_add_i32 s1, s96, -8
	s_and_b32 s97, s1, 2
	s_and_b64 vcc, exec, s[18:19]
	s_waitcnt lgkmcnt(7)
	v_mfma_f32_32x32x16_bf16 v[82:97], v[152:155], v[116:119], 0
	s_waitcnt lgkmcnt(6)
	v_mfma_f32_32x32x16_bf16 v[66:81], v[156:159], v[116:119], 0
	s_waitcnt lgkmcnt(5)
	v_mfma_f32_32x32x16_bf16 v[82:97], v[160:163], v[120:123], v[82:97]
	s_waitcnt lgkmcnt(4)
	v_mfma_f32_32x32x16_bf16 v[66:81], v[164:167], v[120:123], v[66:81]
	s_waitcnt lgkmcnt(3)
	v_mfma_f32_32x32x16_bf16 v[82:97], v[168:171], v[124:127], v[82:97]
	s_waitcnt lgkmcnt(2)
	v_mfma_f32_32x32x16_bf16 v[66:81], v[172:175], v[124:127], v[66:81]
	s_waitcnt lgkmcnt(1)
	v_mfma_f32_32x32x16_bf16 v[82:97], v[176:179], v[128:131], v[82:97]
	s_waitcnt lgkmcnt(0)
	v_mfma_f32_32x32x16_bf16 v[66:81], v[180:183], v[128:131], v[66:81]
	s_cbranch_vccnz .LBB0_968
	s_setprio 0

; #define LAS __attribute__((address_space(3)))
;     __device__ __forceinline__ bool skip(int t) const { const int nb = t >> 2; if (nb >= qb) return 64 * (t & 3) > wq0 + 31; return !__any((int)((sel >> nb) & 1u)); }
; template <bool HAS_POST, class MaskF>
; __device__ __forceinline__ void attn_run(LAS unsigned char* lds, const bf16* Kg, const bf16* Vg, int pitch, int t0, int t1,
;                                          const bf16x8 (&qr)[4], f32x16& o0, f32x16& o1, f32x16& o2, MaskF& mf, const int wv) {
;     ...
;     for (int ts = t0; ts < t1; ts += 2) {
;         const int cur = ((ts - t0) >> 1) & 1;
;         const bool more = (ts + 2 < t1), more2 = (ts + 3 < t1);
;         if (more) { kp += 2 * tstride; kreg0 = *(const v4u*)kp; vp += 2 * tstride; vreg0 = *(const v4u*)vp;
;             if (more2) { kreg1 = *(const v4u*)(kp + tstride); vreg1 = *(const v4u*)(vp + tstride); } }
; #pragma unroll
;         for (int j = 0; j < 2; ++j) {
;             const int t = ts + j;
;             if (t >= t1) break;
;             if (mf.skip(t)) continue;
;             f32x16 p0, p1; const f32x16 zc = {};
;             LAS unsigned char* Kb = lds + (cur * 2 + j) * KBUF + cx.kroff;
;             if (wv < 4) __builtin_amdgcn_s_setprio(1);
; #pragma unroll
;             for (int d0 = 0; d0 < 4; ++d0) {
;                 const bf16x8 a0 = *(const LAS bf16x8*)(Kb + d0 * 32), a1 = *(const LAS bf16x8*)(Kb + 32 * 144 + d0 * 32);
.LBB0_1007:
	s_add_i32 s99, s16, -2
	s_and_b32 s99, s99, 2
	s_mul_i32 s98, s99, 0x2400
	v_add_u32_e32 v106, s98, v167
	ds_read_b128 v[102:105], v106
	ds_read_b128 v[110:113], v106 offset:32
	ds_read_b128 v[50:53], v106 offset:4608
	ds_read_b128 v[132:135], v106 offset:4640
	ds_read_b128 v[136:139], v106 offset:64
	ds_read_b128 v[140:143], v106 offset:4672
	ds_read_b128 v[144:147], v106 offset:96
	ds_read_b128 v[148:151], v106 offset:4704
	s_add_i32 s0, s16, -2
	s_cmp_lt_i32 s16, s33
	s_cselect_b64 s[14:15], -1, 0
	s_cmp_ge_i32 s16, s33
	s_cselect_b64 s[12:13], -1, 0
	s_cmp_lt_i32 s0, s2
	s_cselect_b64 s[4:5], -1, 0
	s_cselect_b64 s[6:7], 0, exec
	s_and_b64 vcc, exec, s[12:13]
	s_cbranch_vccnz .LBB0_1011
	s_mov_b64 s[4:5], 0x4000
	v_lshl_add_u64 v[154:155], v[154:155], 0, s[4:5]
	v_lshl_add_u64 v[156:157], v[156:157], 0, s[4:5]
	global_load_dwordx4 v[82:85], v[154:155], off
	global_load_dwordx4 v[86:89], v[156:157], off
	s_and_b64 vcc, exec, s[6:7]
	s_cbranch_vccnz .LBB0_1010
	s_mov_b64 s[4:5], 0x2000
	v_lshl_add_u64 v[228:229], v[154:155], 0, s[4:5]
	global_load_dwordx4 v[90:93], v[228:229], off
	v_lshl_add_u64 v[228:229], v[156:157], 0, s[4:5]
	global_load_dwordx4 v[94:97], v[228:229], off

; #define LAS __attribute__((address_space(3)))
;     __device__ __forceinline__ bool skip(int t) const { const int nb = t >> 2; if (nb >= qb) return 64 * (t & 3) > wq0 + 31; return !__any((int)((sel >> nb) & 1u)); }
; template <bool HAS_POST, class MaskF>
; __device__ __forceinline__ void attn_run(LAS unsigned char* lds, const bf16* Kg, const bf16* Vg, int pitch, int t0, int t1,
;                                          const bf16x8 (&qr)[4], f32x16& o0, f32x16& o1, f32x16& o2, MaskF& mf, const int wv) {
;     ...
;     for (int ts = t0; ts < t1; ts += 2) {
;         const int cur = ((ts - t0) >> 1) & 1;
;         const bool more = (ts + 2 < t1), more2 = (ts + 3 < t1);
;         if (more) { kp += 2 * tstride; kreg0 = *(const v4u*)kp; vp += 2 * tstride; vreg0 = *(const v4u*)vp;
;             if (more2) { kreg1 = *(const v4u*)(kp + tstride); vreg1 = *(const v4u*)(vp + tstride); } }
; #pragma unroll
;         for (int j = 0; j < 2; ++j) {
;             const int t = ts + j;
;             if (t >= t1) break;
;             if (mf.skip(t)) continue;
;             f32x16 p0, p1; const f32x16 zc = {};
;             LAS unsigned char* Kb = lds + (cur * 2 + j) * KBUF + cx.kroff;
;             if (wv < 4) __builtin_amdgcn_s_setprio(1);
; #pragma unroll
;             for (int d0 = 0; d0 < 4; ++d0) {
;                 const bf16x8 a0 = *(const LAS bf16x8*)(Kb + d0 * 32), a1 = *(const LAS bf16x8*)(Kb + 32 * 144 + d0 * 32);
.LBB0_1077:
	s_and_b32 s99, s4, 2
	s_mul_i32 s98, s99, 0x2400
	v_add_u32_e32 v168, s98, v166
	ds_read_b128 v[50:53], v168
	ds_read_b128 v[102:105], v168 offset:32
	ds_read_b128 v[66:69], v168 offset:4608
	ds_read_b128 v[106:109], v168 offset:4640
	ds_read_b128 v[110:113], v168 offset:64
	ds_read_b128 v[132:135], v168 offset:4672
	ds_read_b128 v[136:139], v168 offset:96
	ds_read_b128 v[140:143], v168 offset:4704
	s_add_u32 s94, s4, 2
	s_addc_u32 s95, s5, 0
	s_cmp_gt_i32 s94, s39
	s_cselect_b64 s[20:21], -1, 0
	s_cmp_le_i32 s94, s39
	s_cselect_b64 s[96:97], -1, 0
	s_cmp_lt_i32 s4, s27
	s_cselect_b64 s[0:1], -1, 0
	s_cselect_b64 s[92:93], 0, exec
	s_and_b64 vcc, exec, s[20:21]
	s_cbranch_vccnz .LBB0_1081
	s_mov_b64 s[0:1], 0xc0000
	v_lshl_add_u64 v[154:155], v[154:155], 0, s[0:1]
	v_lshl_add_u64 v[156:157], v[156:157], 0, s[0:1]
	global_load_dwordx4 v[82:85], v[154:155], off
	global_load_dwordx4 v[86:89], v[156:157], off
	s_and_b64 vcc, exec, s[92:93]
	s_cbranch_vccnz .LBB0_1080
	s_mov_b64 s[0:1], 0x60000
	v_lshl_add_u64 v[228:229], v[154:155], 0, s[0:1]
	global_load_dwordx4 v[90:93], v[228:229], off
	v_lshl_add_u64 v[228:229], v[156:157], 0, s[0:1]
	global_load_dwordx4 v[94:97], v[228:229], off

; #define LAS __attribute__((address_space(3)))
;     __device__ __forceinline__ bool skip(int t) const { const int nb = t >> 2; if (nb >= qb) return 64 * (t & 3) > wq0 + 31; return !__any((int)((sel >> nb) & 1u)); }
; template <bool HAS_POST, class MaskF>
; __device__ __forceinline__ void attn_run(LAS unsigned char* lds, const bf16* Kg, const bf16* Vg, int pitch, int t0, int t1,
;                                          const bf16x8 (&qr)[4], f32x16& o0, f32x16& o1, f32x16& o2, MaskF& mf, const int wv) {
;     ...
;     for (int ts = t0; ts < t1; ts += 2) {
;         const int cur = ((ts - t0) >> 1) & 1;
;         const bool more = (ts + 2 < t1), more2 = (ts + 3 < t1);
;         if (more) { kp += 2 * tstride; kreg0 = *(const v4u*)kp; vp += 2 * tstride; vreg0 = *(const v4u*)vp;
;             if (more2) { kreg1 = *(const v4u*)(kp + tstride); vreg1 = *(const v4u*)(vp + tstride); } }
; #pragma unroll
;         for (int j = 0; j < 2; ++j) {
;             const int t = ts + j;
;             if (t >= t1) break;
;             if (mf.skip(t)) continue;
;             f32x16 p0, p1; const f32x16 zc = {};
;             LAS unsigned char* Kb = lds + (cur * 2 + j) * KBUF + cx.kroff;
;             if (wv < 4) __builtin_amdgcn_s_setprio(1);
; #pragma unroll
;             for (int d0 = 0; d0 < 4; ++d0) {
;                 const bf16x8 a0 = *(const LAS bf16x8*)(Kb + d0 * 32), a1 = *(const LAS bf16x8*)(Kb + 32 * 144 + d0 * 32);
.LBB0_1116:
	s_add_i32 s99, s96, -8
	s_and_b32 s99, s99, 2
	s_mul_i32 s98, s99, 0x2400
	v_add_u32_e32 v54, s98, v207
	ds_read_b128 v[152:155], v54
	ds_read_b128 v[156:159], v54 offset:4608
	ds_read_b128 v[160:163], v54 offset:32
	ds_read_b128 v[164:167], v54 offset:4640
	ds_read_b128 v[168:171], v54 offset:64
	ds_read_b128 v[172:175], v54 offset:4672
	ds_read_b128 v[176:179], v54 offset:96
	ds_read_b128 v[180:183], v54 offset:4704
	s_add_i32 s1, s35, s96
	s_add_i32 s0, s1, -8
	s_add_i32 s1, s1, -6
	s_cmp_le_i32 s1, s39
	s_cselect_b64 s[20:21], -1, 0
	s_cmp_lt_i32 s0, s27
	s_cselect_b64 s[4:5], -1, 0
	s_cselect_b64 s[94:95], 0, exec
	s_cmp_gt_i32 s1, s39
	s_cbranch_scc1 .LBB0_1120
	s_mov_b64 s[4:5], 0xc0000
	v_lshl_add_u64 v[198:199], v[198:199], 0, s[4:5]
	v_lshl_add_u64 v[200:201], v[200:201], 0, s[4:5]
	global_load_dwordx4 v[132:135], v[198:199], off
	global_load_dwordx4 v[136:139], v[200:201], off
	s_and_b64 vcc, exec, s[94:95]
	s_cbranch_vccnz .LBB0_1119
	s_mov_b64 s[4:5], 0x60000
	v_lshl_add_u64 v[228:229], v[198:199], 0, s[4:5]
	global_load_dwordx4 v[140:143], v[228:229], off
	v_lshl_add_u64 v[228:229], v[200:201], 0, s[4:5]
	global_load_dwordx4 v[144:147], v[228:229], off
